# in-projection column tiles processed in reverse order so the LRU columns (read first by mixer pass 1) are written last
# speedup vs baseline: 1.0105x; 1.0105x over previous
.LBB0_221:
	s_ashr_i32 s0, s87, 31
	s_lshr_b32 s0, s0, 29
	s_add_i32 s0, s87, s0
	s_ashr_i32 s1, s0, 3
	s_and_b32 s0, s0, -8
	s_sub_i32 s0, s87, s0
	s_cmp_lt_i32 s0, 0
	s_movk_i32 s16, 0xa1
	s_cselect_b32 s16, s16, 0xa0
	s_mul_i32 s0, s16, s0
	v_mov_b32_e32 v16, v180
	s_add_i32 s0, s0, s1
	s_mul_hi_i32 s1, s0, 0x66666667
	v_ashrrev_i32_e32 v0, 31, v16
	v_lshrrev_b32_e32 v0, 26, v0
	s_lshr_b32 s16, s1, 31
	s_ashr_i32 s1, s1, 7
	v_add_u32_e32 v0, v16, v0
	s_add_i32 s20, s1, s16
	v_ashrrev_i32_e32 v1, 6, v0
	v_bfe_i32 v0, v16, 27, 1
	s_mul_i32 s1, s20, 0x140
	v_lshlrev_b32_e32 v17, 4, v16
	v_lshrrev_b32_e32 v0, 22, v0
	s_sub_i32 s0, s0, s1
	v_add_u32_e32 v0, v17, v0
	s_sext_i32_i16 s1, s0
	v_and_b32_e32 v0, 0xfffffc00, v0
	s_bfe_u32 s1, s1, 0x3001c
	v_sub_u32_e32 v0, v17, v0
	s_add_i32 s1, s0, s1
	v_lshrrev_b32_e32 v2, 4, v0
	s_sext_i32_i16 s16, s1
	s_and_b32 s1, s1, 0xfff8
	v_bitop3_b32 v2, v2, v0, 32 bitop3:0x6c
	s_sub_i32 s0, s0, s1
	v_ashrrev_i32_e32 v3, 31, v2
	s_sext_i32_i16 s0, s0
	v_lshrrev_b32_e32 v3, 26, v3
	s_lshl_b32 s21, s0, 8
	s_lshl_b32 s0, s16, 5
	v_add_u32_e32 v3, v2, v3
	s_and_b32 s0, s0, 0xffffff00
	s_sub_i32 s0, 0x2700, s0
	v_lshlrev_b32_e32 v0, 3, v1
	v_ashrrev_i32_e32 v4, 6, v3
	v_and_b32_e32 v3, 0xc0, v3
	s_ashr_i32 s1, s0, 31
	v_readlane_b32 s52, v254, 60
	v_and_b32_e32 v0, -16, v0
	v_lshlrev_b32_e32 v1, 5, v1
	v_sub_u32_e32 v2, v2, v3
	s_lshl_b64 s[24:25], s[0:1], 13
	v_readlane_b32 s64, v253, 8
	v_add_u32_e32 v0, v4, v0
	v_and_b32_e32 v1, 32, v1
	v_ashrrev_i16_sdwa v2, v145, sext(v2) dst_sel:DWORD dst_unused:UNUSED_PAD src0_sel:DWORD src1_sel:BYTE_0
	v_readlane_b32 s65, v253, 9
	s_add_u32 s16, s64, s24
	v_add_u32_sdwa v128, v1, sext(v2) dst_sel:DWORD dst_unused:UNUSED_PAD src0_sel:DWORD src1_sel:WORD_0
	v_ashrrev_i32_e32 v1, 31, v0
	s_addc_u32 s17, s65, s25
	v_lshlrev_b64 v[130:131], 13, v[0:1]
	v_ashrrev_i32_e32 v129, 31, v128
	v_lshl_add_u64 v[2:3], s[16:17], 0, v[130:131]
	v_lshlrev_b64 v[0:1], 1, v[128:129]
	v_add_u32_e32 v18, 0x2000, v17
	v_lshl_add_u64 v[4:5], v[2:3], 0, v[0:1]
	v_ashrrev_i32_e32 v2, 31, v18
	v_lshrrev_b32_e32 v2, 22, v2
	v_add_u32_e32 v2, v18, v2
	v_ashrrev_i32_e32 v3, 10, v2
	v_mul_i32_i24_e32 v2, 0x400, v3
	v_sub_u32_e32 v2, v18, v2
	v_lshrrev_b32_e32 v6, 4, v2
	v_bitop3_b32 v6, v6, v2, 32 bitop3:0x6c
	v_ashrrev_i32_e32 v7, 31, v6
	v_lshrrev_b32_e32 v7, 26, v7
	v_add_u32_e32 v7, v6, v7
	v_lshlrev_b32_e32 v2, 3, v3
	v_ashrrev_i32_e32 v8, 6, v7
	v_and_b32_e32 v7, 0xc0, v7
	v_add_u32_e32 v146, s33, v17
	v_and_b32_e32 v2, -16, v2
	v_lshlrev_b32_e32 v3, 5, v3
	v_sub_u32_e32 v6, v6, v7
	v_readfirstlane_b32 s1, v146
	v_add_u32_e32 v2, v8, v2
	v_and_b32_e32 v3, 32, v3
	v_ashrrev_i16_sdwa v6, v145, sext(v6) dst_sel:DWORD dst_unused:UNUSED_PAD src0_sel:DWORD src1_sel:BYTE_0
	v_add_u32_e32 v8, s33, v18
	s_mov_b32 m0, s1
	v_add_u32_sdwa v132, v3, sext(v6) dst_sel:DWORD dst_unused:UNUSED_PAD src0_sel:DWORD src1_sel:WORD_0
	v_ashrrev_i32_e32 v3, 31, v2
	v_readfirstlane_b32 s1, v8
	global_load_lds_dwordx4 v[4:5], off
	v_lshlrev_b64 v[134:135], 13, v[2:3]
	s_mov_b32 m0, s1
	s_lshl_b32 s1, s20, 11
	v_lshl_add_u64 v[6:7], s[16:17], 0, v[134:135]
	s_add_i32 s16, s21, s1
	s_ashr_i32 s17, s16, 31
	s_lshl_b64 s[34:35], s[16:17], 13
	v_ashrrev_i32_e32 v133, 31, v132
	s_add_u32 s20, s68, s34
	v_lshlrev_b64 v[2:3], 1, v[132:133]
	s_addc_u32 s21, s69, s35
	v_add_u32_e32 v148, 0, v17
	v_lshl_add_u64 v[6:7], v[6:7], 0, v[2:3]
	v_lshl_add_u64 v[8:9], s[20:21], 0, v[130:131]
	v_readfirstlane_b32 s1, v148
	v_lshl_add_u64 v[10:11], s[20:21], 0, v[134:135]
	v_add_u32_e32 v149, 0x2000, v148
	s_or_b32 s20, s0, 0x80
	v_readfirstlane_b32 s88, v16
	global_load_lds_dwordx4 v[6:7], off
	v_lshl_add_u64 v[8:9], v[8:9], 0, v[0:1]
	s_mov_b32 m0, s1
	v_readfirstlane_b32 s1, v149
	s_ashr_i32 s21, s20, 31
	global_load_lds_dwordx4 v[8:9], off
	s_mov_b32 m0, s1
	s_ashr_i32 s1, s88, 8
	s_lshl_b64 s[20:21], s[20:21], 13
	s_add_u32 s20, s64, s20
	s_addc_u32 s21, s65, s21
	v_lshl_add_u64 v[12:13], s[20:21], 0, v[130:131]
	v_lshl_add_u64 v[14:15], s[20:21], 0, v[134:135]
	s_or_b32 s20, s16, 0x80
	s_ashr_i32 s21, s20, 31
	v_add_u32_e32 v151, s80, v17
	s_lshl_b64 s[20:21], s[20:21], 13
	v_lshl_add_u64 v[10:11], v[10:11], 0, v[2:3]
	v_readfirstlane_b32 s17, v151
	v_add_u32_e32 v18, s80, v18
	s_add_u32 s20, s68, s20
	global_load_lds_dwordx4 v[10:11], off
	v_lshl_add_u64 v[12:13], v[12:13], 0, v[0:1]
	s_mov_b32 m0, s17
	v_readfirstlane_b32 s17, v18
	s_addc_u32 s21, s69, s21
	v_add_u32_e32 v153, 0x4000, v148
	global_load_lds_dwordx4 v[12:13], off
	v_lshl_add_u64 v[14:15], v[14:15], 0, v[2:3]
	s_mov_b32 m0, s17
	v_lshl_add_u64 v[18:19], s[20:21], 0, v[130:131]
	v_readfirstlane_b32 s17, v153
	global_load_lds_dwordx4 v[14:15], off
	v_lshl_add_u64 v[18:19], v[18:19], 0, v[0:1]
	s_mov_b32 m0, s17
	v_add_u32_e32 v154, 0x6000, v148
	global_load_lds_dwordx4 v[18:19], off
	v_lshl_add_u64 v[18:19], s[20:21], 0, v[134:135]
	v_readfirstlane_b32 s17, v154
	v_lshl_add_u64 v[18:19], v[18:19], 0, v[2:3]
	s_mov_b32 m0, s17
	s_cmp_lg_u32 s1, 1
	global_load_lds_dwordx4 v[18:19], off
	v_readlane_b32 s53, v254, 61
	v_readlane_b32 s54, v254, 62
	v_readlane_b32 s55, v254, 63
	v_readlane_b32 s56, v253, 0
	v_readlane_b32 s57, v253, 1
	v_readlane_b32 s58, v253, 2
	v_readlane_b32 s59, v253, 3
	v_readlane_b32 s60, v253, 4
	v_readlane_b32 s61, v253, 5
	v_readlane_b32 s62, v253, 6
	v_readlane_b32 s63, v253, 7
	v_readlane_b32 s66, v253, 10
	v_readlane_b32 s67, v253, 11
	s_cbranch_scc1 .LBB0_223
	s_barrier

.LBB0_931:
	s_ashr_i32 s0, s58, 31
	s_lshr_b32 s0, s0, 29
	s_add_i32 s0, s58, s0
	s_ashr_i32 s1, s0, 3
	s_and_b32 s0, s0, -8
	s_sub_i32 s0, s58, s0
	s_cmp_lt_i32 s0, 0
	s_movk_i32 s24, 0xa1
	s_cselect_b32 s24, s24, 0xa0
	s_mul_i32 s0, s24, s0
	v_mov_b32_e32 v16, v180
	s_add_i32 s0, s0, s1
	s_mul_hi_i32 s1, s0, 0x66666667
	v_ashrrev_i32_e32 v0, 31, v16
	v_lshrrev_b32_e32 v0, 26, v0
	s_lshr_b32 s24, s1, 31
	s_ashr_i32 s1, s1, 7
	v_add_u32_e32 v0, v16, v0
	s_add_i32 s34, s1, s24
	v_ashrrev_i32_e32 v1, 6, v0
	v_bfe_i32 v0, v16, 27, 1
	s_mul_i32 s1, s34, 0x140
	v_lshlrev_b32_e32 v17, 4, v16
	v_lshrrev_b32_e32 v0, 22, v0
	s_sub_i32 s0, s0, s1
	v_add_u32_e32 v0, v17, v0
	s_sext_i32_i16 s1, s0
	v_and_b32_e32 v0, 0xfffffc00, v0
	s_bfe_u32 s1, s1, 0x3001c
	v_sub_u32_e32 v0, v17, v0
	s_add_i32 s1, s0, s1
	v_lshrrev_b32_e32 v2, 4, v0
	s_sext_i32_i16 s24, s1
	s_and_b32 s1, s1, 0xfff8
	v_bitop3_b32 v2, v2, v0, 32 bitop3:0x6c
	s_sub_i32 s0, s0, s1
	v_ashrrev_i32_e32 v3, 31, v2
	s_sext_i32_i16 s0, s0
	v_lshrrev_b32_e32 v3, 26, v3
	s_lshl_b32 s35, s0, 8
	s_lshl_b32 s0, s24, 5
	v_add_u32_e32 v3, v2, v3
	s_and_b32 s0, s0, 0xffffff00
	s_sub_i32 s0, 0x2700, s0
	v_lshlrev_b32_e32 v0, 3, v1
	v_ashrrev_i32_e32 v4, 6, v3
	v_and_b32_e32 v3, 0xc0, v3
	s_ashr_i32 s1, s0, 31
	v_and_b32_e32 v0, -16, v0
	v_lshlrev_b32_e32 v1, 5, v1
	v_sub_u32_e32 v2, v2, v3
	s_lshl_b64 s[90:91], s[0:1], 13
	v_add_u32_e32 v0, v4, v0
	v_and_b32_e32 v1, 32, v1
	v_ashrrev_i16_sdwa v2, v145, sext(v2) dst_sel:DWORD dst_unused:UNUSED_PAD src0_sel:DWORD src1_sel:BYTE_0
	s_add_u32 s24, s33, s90
	v_add_u32_sdwa v128, v1, sext(v2) dst_sel:DWORD dst_unused:UNUSED_PAD src0_sel:DWORD src1_sel:WORD_0
	v_ashrrev_i32_e32 v1, 31, v0
	s_addc_u32 s25, s52, s91
	v_lshlrev_b64 v[130:131], 13, v[0:1]
	v_ashrrev_i32_e32 v129, 31, v128
	v_lshl_add_u64 v[2:3], s[24:25], 0, v[130:131]
	v_lshlrev_b64 v[0:1], 1, v[128:129]
	v_add_u32_e32 v18, 0x2000, v17
	v_lshl_add_u64 v[4:5], v[2:3], 0, v[0:1]
	v_ashrrev_i32_e32 v2, 31, v18
	v_lshrrev_b32_e32 v2, 22, v2
	v_add_u32_e32 v2, v18, v2
	v_ashrrev_i32_e32 v3, 10, v2
	v_mul_i32_i24_e32 v2, 0x400, v3
	v_sub_u32_e32 v2, v18, v2
	v_lshrrev_b32_e32 v6, 4, v2
	v_bitop3_b32 v6, v6, v2, 32 bitop3:0x6c
	v_ashrrev_i32_e32 v7, 31, v6
	v_lshrrev_b32_e32 v7, 26, v7
	v_add_u32_e32 v7, v6, v7
	v_lshlrev_b32_e32 v2, 3, v3
	v_ashrrev_i32_e32 v8, 6, v7
	v_and_b32_e32 v7, 0xc0, v7
	v_add_u32_e32 v146, s53, v17
	v_and_b32_e32 v2, -16, v2
	v_lshlrev_b32_e32 v3, 5, v3
	v_sub_u32_e32 v6, v6, v7
	v_readfirstlane_b32 s1, v146
	v_add_u32_e32 v2, v8, v2
	v_and_b32_e32 v3, 32, v3
	v_ashrrev_i16_sdwa v6, v145, sext(v6) dst_sel:DWORD dst_unused:UNUSED_PAD src0_sel:DWORD src1_sel:BYTE_0
	v_add_u32_e32 v8, s53, v18
	s_mov_b32 m0, s1
	v_add_u32_sdwa v132, v3, sext(v6) dst_sel:DWORD dst_unused:UNUSED_PAD src0_sel:DWORD src1_sel:WORD_0
	v_ashrrev_i32_e32 v3, 31, v2
	v_readfirstlane_b32 s1, v8
	global_load_lds_dwordx4 v[4:5], off
	v_lshlrev_b64 v[134:135], 13, v[2:3]
	s_mov_b32 m0, s1
	s_lshl_b32 s1, s34, 11
	v_lshl_add_u64 v[6:7], s[24:25], 0, v[134:135]
	s_add_i32 s24, s35, s1
	s_ashr_i32 s25, s24, 31
	s_lshl_b64 s[92:93], s[24:25], 13
	v_ashrrev_i32_e32 v133, 31, v132
	s_add_u32 s34, s64, s92
	v_lshlrev_b64 v[2:3], 1, v[132:133]
	s_addc_u32 s35, s65, s93
	v_add_u32_e32 v148, 0, v17
	v_lshl_add_u64 v[6:7], v[6:7], 0, v[2:3]
	v_lshl_add_u64 v[8:9], s[34:35], 0, v[130:131]
	v_readfirstlane_b32 s1, v148
	v_lshl_add_u64 v[10:11], s[34:35], 0, v[134:135]
	v_add_u32_e32 v149, 0x2000, v148
	s_or_b32 s34, s0, 0x80
	v_readfirstlane_b32 s59, v16
	global_load_lds_dwordx4 v[6:7], off
	v_lshl_add_u64 v[8:9], v[8:9], 0, v[0:1]
	s_mov_b32 m0, s1
	v_readfirstlane_b32 s1, v149
	s_ashr_i32 s35, s34, 31
	global_load_lds_dwordx4 v[8:9], off
	s_mov_b32 m0, s1
	s_ashr_i32 s1, s59, 8
	s_lshl_b64 s[34:35], s[34:35], 13
	s_add_u32 s34, s33, s34
	s_addc_u32 s35, s52, s35
	v_lshl_add_u64 v[12:13], s[34:35], 0, v[130:131]
	v_lshl_add_u64 v[14:15], s[34:35], 0, v[134:135]
	s_or_b32 s34, s24, 0x80
	s_ashr_i32 s35, s34, 31
	v_add_u32_e32 v151, s54, v17
	s_lshl_b64 s[34:35], s[34:35], 13
	v_lshl_add_u64 v[10:11], v[10:11], 0, v[2:3]
	v_readfirstlane_b32 s25, v151
	v_add_u32_e32 v18, s54, v18
	s_add_u32 s34, s64, s34
	global_load_lds_dwordx4 v[10:11], off
	v_lshl_add_u64 v[12:13], v[12:13], 0, v[0:1]
	s_mov_b32 m0, s25
	v_readfirstlane_b32 s25, v18
	s_addc_u32 s35, s65, s35
	v_add_u32_e32 v153, 0x4000, v148
	global_load_lds_dwordx4 v[12:13], off
	v_lshl_add_u64 v[14:15], v[14:15], 0, v[2:3]
	s_mov_b32 m0, s25
	v_lshl_add_u64 v[18:19], s[34:35], 0, v[130:131]
	v_readfirstlane_b32 s25, v153
	global_load_lds_dwordx4 v[14:15], off
	v_lshl_add_u64 v[18:19], v[18:19], 0, v[0:1]
	s_mov_b32 m0, s25
	v_add_u32_e32 v154, 0x6000, v148
	global_load_lds_dwordx4 v[18:19], off
	v_lshl_add_u64 v[18:19], s[34:35], 0, v[134:135]
	v_readfirstlane_b32 s25, v154
	v_lshl_add_u64 v[18:19], v[18:19], 0, v[2:3]
	s_mov_b32 m0, s25
	s_cmp_lg_u32 s1, 1
	global_load_lds_dwordx4 v[18:19], off
	s_cbranch_scc1 .LBB0_933
	s_barrier
